# flag hand-off instead of cg grid sync at seam 0; L1 invalidate of local/half barriers overlapped with the wait; pipelined row passes
# speedup vs baseline: 1.0174x; 1.0174x over previous
; __device__ __forceinline__ void p0_prologue(const Args& a, LAS unsigned char* lds, int G) {
;     ...
;     for (int e = blockIdx.x * NTHR + tid; e < 256 * 16; e += G * NTHR) {
;         const int pos = e >> 4, i = e & 15;
;         const float inv = exp2f(-(float)i * (13.287712379549449f / 16.0f));
;         const float ang = (float)pos * inv;
;         const double rev = (double)ang * 0.15915494309189533577;
;         const float fr = (float)(rev - floor(rev));
;         rope[2 * e] = __builtin_amdgcn_cosf(fr); rope[2 * e + 1] = __builtin_amdgcn_sinf(fr);
; __global__ void __launch_bounds__(NTHR, 2) fwd_megakernel(Args a) {
;     ...
;     if (threadIdx.x < 4) bst[threadIdx.x] = 0u;
;     __syncthreads();
;     if (lo == 0 && hi > 1) { if (blockIdx.x == 0) for (int w = threadIdx.x; w < XL_WORDS; w += NTHR) __hip_atomic_store((unsigned*)(ws + WS_CTL) + w, 0u, __ATOMIC_RELAXED, __HIP_MEMORY_SCOPE_AGENT); }
.LBB0_4:
	v_add_u32_e32 v1, 0x200, v1
	v_cmp_lt_u32_e32 vcc, s10, v1
	global_store_dword v[4:5], v3, off sc1
	s_or_b64 s[4:5], vcc, s[4:5]
	v_lshl_add_u64 v[4:5], v[4:5], 0, s[6:7]
	s_andn2_b64 exec, exec, s[4:5]
	s_cbranch_execnz .LBB0_4
	s_or_b64 exec, exec, s[4:5]
	s_waitcnt vmcnt(0)
	s_barrier
	v_cmp_eq_u32_e32 vcc, 0, v206
	s_and_saveexec_b64 s[4:5], vcc
	s_cbranch_execz .Lflag_set_done
	buffer_wbl2 sc1
	s_waitcnt vmcnt(0)
	v_mov_b32_e32 v4, 0x5aa0
	v_mov_b32_e32 v2, 0x5eed1e57
	v_mov_b32_e32 v3, 0x3c0ffee5
	global_atomic_add_x2 v4, v[2:3], s[50:51]
.Lflag_set_done:
	s_or_b64 exec, exec, s[4:5]
.LBB0_6:
	s_load_dwordx16 s[12:27], s[0:1], 0x0
	s_add_u32 s96, s50, 0x100000
	s_addc_u32 s97, s51, 0
	s_add_u32 s94, s50, 0x120000
	s_addc_u32 s95, s51, 0
	s_waitcnt lgkmcnt(0)
	v_writelane_b32 v252, s12, 17
	s_add_u32 s92, s50, 0x130000
	s_addc_u32 s93, s51, 0
	v_writelane_b32 v252, s13, 18
	v_writelane_b32 v252, s14, 19
	v_writelane_b32 v252, s15, 20
	v_writelane_b32 v252, s16, 21
	v_writelane_b32 v252, s17, 22
	v_writelane_b32 v252, s18, 23
	s_add_u32 s90, s50, 0x200000
	v_writelane_b32 v252, s19, 24
	s_addc_u32 s91, s51, 0
	v_writelane_b32 v252, s20, 25
	s_add_u32 s34, s50, 0x600000
	v_writelane_b32 v252, s21, 26
	s_addc_u32 s35, s51, 0
	v_writelane_b32 v252, s22, 27
	s_cmp_lt_i32 s84, 1
	v_writelane_b32 v252, s23, 28
	s_cselect_b64 s[0:1], -1, 0
	s_cmp_gt_i32 s85, 0
	v_writelane_b32 v252, s24, 29
	s_cselect_b64 s[4:5], -1, 0
	v_writelane_b32 v252, s25, 30
	s_and_b64 s[0:1], s[0:1], s[4:5]
	v_writelane_b32 v252, s26, 31
	s_andn2_b64 vcc, exec, s[0:1]
	s_mov_b64 s[0:1], 0
	v_writelane_b32 v252, s27, 32
	s_cbranch_vccnz .LBB0_37
	v_lshl_add_u32 v2, s2, 9, v206
	s_movk_i32 s0, 0x1000
	v_readfirstlane_b32 s14, v206
	v_cmp_gt_i32_e32 vcc, s0, v2
	s_and_saveexec_b64 s[0:1], vcc
	s_cbranch_execz .LBB0_10
	v_and_b32_e32 v1, 15, v206
	v_cvt_f32_ubyte0_e32 v1, v1
	v_mul_f32_e32 v3, 0xbf549a78, v1
	s_mov_b32 s4, 0xc2fc0000
	v_mov_b32_e32 v4, 0x42800000
	v_cmp_gt_f32_e32 vcc, s4, v3
	s_mov_b32 s6, 0x6dc9c883
	s_lshl_b32 s10, s86, 9
	v_cndmask_b32_e32 v3, 0, v4, vcc
	v_fmac_f32_e32 v3, 0xbf549a78, v1
	v_exp_f32_e32 v1, v3
	v_not_b32_e32 v3, 63
	v_cndmask_b32_e32 v3, 0, v3, vcc
	s_lshl_b32 s11, s86, 10
	v_ldexp_f32 v1, v1, v3
	v_lshlrev_b32_e32 v3, 1, v206
	v_lshl_add_u32 v4, s2, 10, v3
	s_mov_b64 s[4:5], 0
	s_mov_b32 s7, 0x3fc45f30
	s_movk_i32 s12, 0xfff
	v_mov_b32_e32 v3, v2

; #define LAS __attribute__((address_space(3)))
; __device__ __forceinline__ unsigned xb_add(unsigned* p, unsigned v) { return __hip_atomic_fetch_add(p, v, __ATOMIC_RELAXED, __HIP_MEMORY_SCOPE_AGENT); }
; __device__ __forceinline__ unsigned xb_xcc_id() { return (unsigned)__builtin_amdgcn_s_getreg((3 << 11) | 20) & 0xFu; }
; __device__ __forceinline__ XcdBarrier xcd_barrier_post(unsigned* bar, volatile LAS unsigned* st) {
;     XcdBarrier b; b.bar = bar; b.x = xb_xcc_id(); b.st = st;
;     if (threadIdx.x == 0) st[2] = xb_add(&bar[XB_XCNT(b.x)], 1u);
; __global__ void __launch_bounds__(NTHR, 2) fwd_megakernel(Args a) {
;     ...
;         grid.sync();
;         bar = xcd_barrier_post((unsigned*)(ws + WS_CTL), bst);
.LBB0_37:
	s_add_u32 s36, s50, 0x2a00000
	s_addc_u32 s37, s51, 0
	s_add_u32 s4, s50, 0x3000000
	s_addc_u32 s5, s51, 0
	v_writelane_b32 v252, s4, 33
	s_andn2_b64 vcc, exec, s[0:1]
	s_nop 0
	v_writelane_b32 v252, s5, 34
	s_cbranch_vccnz .LBB0_63
	v_lshrrev_b32_e32 v1, 20, v0
	v_lshrrev_b32_e32 v0, 10, v0
	v_or_b32_e32 v0, v0, v1
	s_movk_i32 s0, 0x3ff
	v_and_or_b32 v0, v0, s0, v206
	v_cmp_eq_u32_e32 vcc, 0, v0
	s_barrier
	s_and_saveexec_b64 s[0:1], vcc
	s_cbranch_execz .LBB0_48
	s_add_u32 s4, s50, 0x5aa0
	s_addc_u32 s5, s51, 0
	v_mov_b32_e32 v2, 0
	s_mov_b32 s6, 0x5eed1e57
	s_mov_b32 s7, 0x3c0ffee5
	s_mov_b32 s8, 0
.Lflag_spin:
	global_load_dwordx2 v[0:1], v2, s[4:5] sc1
	s_waitcnt vmcnt(0)
	v_cmp_eq_u32_e32 vcc, s6, v0
	v_cmp_eq_u32_e64 s[60:61], s7, v1
	s_nop 1
	s_and_b64 vcc, vcc, s[60:61]
	s_cbranch_vccnz .Lflag_done
	s_add_u32 s8, s8, 1
	s_cmp_lt_u32 s8, 0x40000
	s_cbranch_scc0 .Lflag_done
	s_sleep 1
	s_branch .Lflag_spin
.Lflag_done:
.LBB0_48:
	s_or_b64 exec, exec, s[0:1]
	s_barrier
	s_getreg_b32 s0, hwreg(HW_REG_XCC_ID, 0, 4)
	s_and_b32 s33, s0, 15
	v_cmp_eq_u32_e64 s[0:1], 0, v206
	s_and_saveexec_b64 s[4:5], s[0:1]
	s_cbranch_execz .LBB0_52
	s_mov_b64 s[8:9], exec
	v_mbcnt_lo_u32_b32 v0, s8, 0
	v_mbcnt_hi_u32_b32 v0, s9, v0
	v_cmp_eq_u32_e32 vcc, 0, v0
	s_and_saveexec_b64 s[6:7], vcc
	s_cbranch_execz .LBB0_51
	s_lshl_b32 s10, s33, 8
	s_bcnt1_i32_b64 s8, s[8:9]
	v_mov_b32_e32 v1, s10
	v_mov_b32_e32 v2, s8
	global_atomic_add v1, v1, v2, s[50:51] offset:1024 sc0

; __device__ __forceinline__ unsigned xb_ld(unsigned* p)              { return __hip_atomic_load(p, __ATOMIC_RELAXED, __HIP_MEMORY_SCOPE_AGENT); }
; __device__ __forceinline__ unsigned xb_add(unsigned* p, unsigned v) { return __hip_atomic_fetch_add(p, v, __ATOMIC_RELAXED, __HIP_MEMORY_SCOPE_AGENT); }
; #define XB_SPIN(cond, bar) do { unsigned _sp = 0; while (cond) { __builtin_amdgcn_s_sleep(1); \
;     if ((++_sp & 255u) == 0u) { if (xb_ld(&(bar)[XB_TMO])) break; if (_sp > XB_SPIN_CAP) { atomicAdd(&(bar)[XB_TMO], 1u); break; } } } } while (0)
; __device__ __forceinline__ void xcd_half_barrier(const XcdBarrier& b, unsigned h) {
;     ...
;         const unsigned old = xb_add(&bar[XB_XSUB(b.x)], 1u);
;         const unsigned gen = old / nloc;
;         if (old + 1u == (gen + 1u) * nloc) {
;             __builtin_amdgcn_fence(__ATOMIC_RELEASE, "agent");
;             asm volatile("s_waitcnt vmcnt(0)" ::: "memory");
;             const unsigned og = xb_add(&bar[XH_TOP(h)], 1u);
;             const unsigned tg = og / nx;
;             if (og + 1u == (tg + 1u) * nx) xb_add(&bar[XH_TOPGEN(h)], 1u);
;             else XB_SPIN(xb_ld(&bar[XH_TOPGEN(h)]) == tg, bar);
;             __builtin_amdgcn_fence(__ATOMIC_ACQUIRE, "agent");
;             xb_add(&bar[XB_XGEN(b.x)], 1u);
;             asm volatile("s_waitcnt vmcnt(0)" ::: "memory");
;         } else {
;             XB_SPIN(xb_ld(&bar[XB_XGEN(b.x)]) == gen, bar);
.LBB0_286:
	s_or_b64 exec, exec, s[14:15]
	s_waitcnt lgkmcnt(0)
	v_cvt_f32_u32_e32 v3, v1
	s_waitcnt vmcnt(0)
	v_readfirstlane_b32 s12, v2
	v_sub_u32_e32 v2, 0, v1
	v_rcp_iflag_f32_e32 v3, v3
	v_add_u32_e32 v4, s12, v0
	v_mul_f32_e32 v3, 0x4f7ffffe, v3
	v_cvt_u32_f32_e32 v3, v3
	v_mul_lo_u32 v0, v2, v3
	v_mul_hi_u32 v0, v3, v0
	v_add_u32_e32 v0, v3, v0
	v_mul_hi_u32 v0, v4, v0
	v_mul_lo_u32 v2, v0, v1
	v_sub_u32_e32 v2, v4, v2
	v_add_u32_e32 v3, 1, v0
	v_cmp_ge_u32_e32 vcc, v2, v1
	s_nop 1
	v_cndmask_b32_e32 v0, v0, v3, vcc
	v_sub_u32_e32 v3, v2, v1
	v_cndmask_b32_e32 v2, v2, v3, vcc
	v_add_u32_e32 v3, 1, v0
	v_cmp_ge_u32_e32 vcc, v2, v1
	v_add_u32_e32 v2, 1, v4
	s_nop 0
	v_cndmask_b32_e32 v0, v0, v3, vcc
	v_mul_lo_u32 v3, v1, v0
	v_add_u32_e32 v1, v3, v1
	v_cmp_ne_u32_e32 vcc, v2, v1
	s_and_saveexec_b64 s[12:13], vcc
	s_xor_b64 s[12:13], exec, s[12:13]
	s_cbranch_execz .LBB0_300
	buffer_inv sc1
	v_mov_b32_e32 v1, 0x2000
	global_load_dword v1, v1, s[0:1] offset:1024 sc1
	s_add_u32 s18, s0, 0x2400
	s_addc_u32 s19, s1, 0
	s_waitcnt vmcnt(0)
	v_cmp_eq_u32_e32 vcc, v1, v0
	s_and_saveexec_b64 s[14:15], vcc
	s_cbranch_execz .LBB0_299
	s_mov_b32 s30, 1
	s_mov_b64 s[20:21], 0
	v_mov_b32_e32 v1, 0
	s_branch .LBB0_290

; __device__ __forceinline__ unsigned xb_ld(unsigned* p)              { return __hip_atomic_load(p, __ATOMIC_RELAXED, __HIP_MEMORY_SCOPE_AGENT); }
; #define XB_SPIN(cond, bar) do { unsigned _sp = 0; while (cond) { __builtin_amdgcn_s_sleep(1); \
;     if ((++_sp & 255u) == 0u) { if (xb_ld(&(bar)[XB_TMO])) break; if (_sp > XB_SPIN_CAP) { atomicAdd(&(bar)[XB_TMO], 1u); break; } } } } while (0)
; __device__ __forceinline__ void xcd_half_barrier(const XcdBarrier& b, unsigned h) {
;     ...
;             XB_SPIN(xb_ld(&bar[XB_XGEN(b.x)]) == gen, bar);
;             __builtin_amdgcn_fence(__ATOMIC_ACQUIRE, "agent");
;             asm volatile("s_waitcnt vmcnt(0)" ::: "memory");
.LBB0_299:
	s_or_b64 exec, exec, s[14:15]
	s_waitcnt vmcnt(0)
	s_waitcnt vmcnt(0)

; __device__ __forceinline__ unsigned xb_ld(unsigned* p)              { return __hip_atomic_load(p, __ATOMIC_RELAXED, __HIP_MEMORY_SCOPE_AGENT); }
; __device__ __forceinline__ unsigned xb_add(unsigned* p, unsigned v) { return __hip_atomic_fetch_add(p, v, __ATOMIC_RELAXED, __HIP_MEMORY_SCOPE_AGENT); }
; #define XB_SPIN(cond, bar) do { unsigned _sp = 0; while (cond) { __builtin_amdgcn_s_sleep(1); \
;     if ((++_sp & 255u) == 0u) { if (xb_ld(&(bar)[XB_TMO])) break; if (_sp > XB_SPIN_CAP) { atomicAdd(&(bar)[XB_TMO], 1u); break; } } } } while (0)
; __device__ __forceinline__ void xcd_half_barrier(const XcdBarrier& b, unsigned h) {
;     ...
;         const unsigned old = xb_add(&bar[XB_XSUB(b.x)], 1u);
;         const unsigned gen = old / nloc;
;         if (old + 1u == (gen + 1u) * nloc) {
;             __builtin_amdgcn_fence(__ATOMIC_RELEASE, "agent");
;             asm volatile("s_waitcnt vmcnt(0)" ::: "memory");
;             const unsigned og = xb_add(&bar[XH_TOP(h)], 1u);
;             const unsigned tg = og / nx;
;             if (og + 1u == (tg + 1u) * nx) xb_add(&bar[XH_TOPGEN(h)], 1u);
;             else XB_SPIN(xb_ld(&bar[XH_TOPGEN(h)]) == tg, bar);
;             __builtin_amdgcn_fence(__ATOMIC_ACQUIRE, "agent");
;             xb_add(&bar[XB_XGEN(b.x)], 1u);
;             asm volatile("s_waitcnt vmcnt(0)" ::: "memory");
;         } else {
;             XB_SPIN(xb_ld(&bar[XB_XGEN(b.x)]) == gen, bar);
.LBB0_460:
	s_or_b64 exec, exec, s[14:15]
	s_waitcnt lgkmcnt(0)
	v_cvt_f32_u32_e32 v3, v1
	s_waitcnt vmcnt(0)
	v_readfirstlane_b32 s12, v2
	v_sub_u32_e32 v2, 0, v1
	v_rcp_iflag_f32_e32 v3, v3
	v_add_u32_e32 v4, s12, v0
	v_mul_f32_e32 v3, 0x4f7ffffe, v3
	v_cvt_u32_f32_e32 v3, v3
	v_mul_lo_u32 v0, v2, v3
	v_mul_hi_u32 v0, v3, v0
	v_add_u32_e32 v0, v3, v0
	v_mul_hi_u32 v0, v4, v0
	v_mul_lo_u32 v2, v0, v1
	v_sub_u32_e32 v2, v4, v2
	v_add_u32_e32 v3, 1, v0
	v_cmp_ge_u32_e32 vcc, v2, v1
	s_nop 1
	v_cndmask_b32_e32 v0, v0, v3, vcc
	v_sub_u32_e32 v3, v2, v1
	v_cndmask_b32_e32 v2, v2, v3, vcc
	v_add_u32_e32 v3, 1, v0
	v_cmp_ge_u32_e32 vcc, v2, v1
	v_add_u32_e32 v2, 1, v4
	s_nop 0
	v_cndmask_b32_e32 v0, v0, v3, vcc
	v_mul_lo_u32 v3, v1, v0
	v_add_u32_e32 v1, v3, v1
	v_cmp_ne_u32_e32 vcc, v2, v1
	s_and_saveexec_b64 s[12:13], vcc
	s_xor_b64 s[12:13], exec, s[12:13]
	s_cbranch_execz .LBB0_474
	buffer_inv sc1
	v_mov_b32_e32 v1, 0x2000
	global_load_dword v1, v1, s[8:9] offset:1024 sc1
	s_add_u32 s20, s8, 0x2400
	s_addc_u32 s21, s9, 0
	s_waitcnt vmcnt(0)
	v_cmp_eq_u32_e32 vcc, v1, v0
	s_and_saveexec_b64 s[14:15], vcc
	s_cbranch_execz .LBB0_473
	s_mov_b32 s40, 1
	s_mov_b64 s[22:23], 0
	v_mov_b32_e32 v1, 0
	s_branch .LBB0_464

; __device__ __forceinline__ unsigned xb_ld(unsigned* p)              { return __hip_atomic_load(p, __ATOMIC_RELAXED, __HIP_MEMORY_SCOPE_AGENT); }
; __device__ __forceinline__ unsigned xb_add(unsigned* p, unsigned v) { return __hip_atomic_fetch_add(p, v, __ATOMIC_RELAXED, __HIP_MEMORY_SCOPE_AGENT); }
; #define XB_SPIN(cond, bar) do { unsigned _sp = 0; while (cond) { __builtin_amdgcn_s_sleep(1); \
;     if ((++_sp & 255u) == 0u) { if (xb_ld(&(bar)[XB_TMO])) break; if (_sp > XB_SPIN_CAP) { atomicAdd(&(bar)[XB_TMO], 1u); break; } } } } while (0)
; __device__ __forceinline__ void xcd_local_barrier(const XcdBarrier& b) {
;     ...
;         const unsigned nloc = b.st[0];
;         const unsigned old = xb_add(&bar[XL_SUB(b.x)], 1u);
;         const unsigned gen = old / nloc;
;         if (old + 1u == (gen + 1u) * nloc) xb_add(&bar[XL_GEN(b.x)], 1u);
;         else XB_SPIN(xb_ld(&bar[XL_GEN(b.x)]) == gen, bar);
;         __builtin_amdgcn_fence(__ATOMIC_ACQUIRE, "agent");
;         asm volatile("s_waitcnt vmcnt(0)" ::: "memory");
.LBB0_623:
	s_or_b64 exec, exec, s[18:19]
	buffer_inv sc1
	s_waitcnt lgkmcnt(0)
	v_cvt_f32_u32_e32 v3, v0
	s_waitcnt vmcnt(1)
	v_readfirstlane_b32 s12, v2
	s_mov_b64 s[18:19], -1
	v_rcp_iflag_f32_e32 v3, v3
	v_add_u32_e32 v1, s12, v1
	v_add_u32_e32 v4, 1, v1
	s_add_u32 s12, s8, 0x4600
	v_mul_f32_e32 v2, 0x4f7ffffe, v3
	v_cvt_u32_f32_e32 v2, v2
	v_sub_u32_e32 v3, 0, v0
	s_addc_u32 s13, s9, 0
	v_mul_lo_u32 v3, v3, v2
	v_mul_hi_u32 v3, v2, v3
	v_add_u32_e32 v2, v2, v3
	v_mul_hi_u32 v2, v1, v2
	v_mul_lo_u32 v3, v2, v0
	v_sub_u32_e32 v1, v1, v3
	v_add_u32_e32 v5, 1, v2
	v_cmp_ge_u32_e32 vcc, v1, v0
	v_sub_u32_e32 v3, v1, v0
	s_nop 0
	v_cndmask_b32_e32 v2, v2, v5, vcc
	v_cndmask_b32_e32 v1, v1, v3, vcc
	v_add_u32_e32 v3, 1, v2
	v_cmp_ge_u32_e32 vcc, v1, v0
	s_nop 1
	v_cndmask_b32_e32 v2, v2, v3, vcc
	v_mul_lo_u32 v1, v0, v2
	v_add_u32_e32 v0, v1, v0
	v_cmp_ne_u32_e32 vcc, v4, v0
	v_mov_b64_e32 v[0:1], s[12:13]
	s_and_saveexec_b64 s[8:9], vcc
	s_cbranch_execz .LBB0_635
	v_mov_b32_e32 v0, 0
	global_load_dword v1, v0, s[12:13] sc1
	s_mov_b64 s[22:23], 0
	s_waitcnt vmcnt(0)
	v_cmp_eq_u32_e32 vcc, v1, v2
	s_and_saveexec_b64 s[20:21], vcc
	s_cbranch_execz .LBB0_634
	s_add_u32 s18, s50, 0x200
	s_addc_u32 s19, s51, 0
	s_mov_b32 s38, 1
	s_branch .LBB0_627

; __device__ __forceinline__ unsigned xb_ld(unsigned* p)              { return __hip_atomic_load(p, __ATOMIC_RELAXED, __HIP_MEMORY_SCOPE_AGENT); }
; #define XB_SPIN(cond, bar) do { unsigned _sp = 0; while (cond) { __builtin_amdgcn_s_sleep(1); \
;     if ((++_sp & 255u) == 0u) { if (xb_ld(&(bar)[XB_TMO])) break; if (_sp > XB_SPIN_CAP) { atomicAdd(&(bar)[XB_TMO], 1u); break; } } } } while (0)
; __device__ __forceinline__ void xcd_local_barrier(const XcdBarrier& b) {
;     ...
;         else XB_SPIN(xb_ld(&bar[XL_GEN(b.x)]) == gen, bar);
;         __builtin_amdgcn_fence(__ATOMIC_ACQUIRE, "agent");
;         asm volatile("s_waitcnt vmcnt(0)" ::: "memory");
.LBB0_637:
	s_or_b64 exec, exec, s[8:9]
	s_waitcnt vmcnt(0)
	s_waitcnt vmcnt(0)

; __device__ __forceinline__ unsigned xb_ld(unsigned* p)              { return __hip_atomic_load(p, __ATOMIC_RELAXED, __HIP_MEMORY_SCOPE_AGENT); }
; __device__ __forceinline__ unsigned xb_add(unsigned* p, unsigned v) { return __hip_atomic_fetch_add(p, v, __ATOMIC_RELAXED, __HIP_MEMORY_SCOPE_AGENT); }
; #define XB_SPIN(cond, bar) do { unsigned _sp = 0; while (cond) { __builtin_amdgcn_s_sleep(1); \
;     if ((++_sp & 255u) == 0u) { if (xb_ld(&(bar)[XB_TMO])) break; if (_sp > XB_SPIN_CAP) { atomicAdd(&(bar)[XB_TMO], 1u); break; } } } } while (0)
; __device__ __forceinline__ void xcd_local_barrier(const XcdBarrier& b) {
;     ...
;         const unsigned nloc = b.st[0];
;         const unsigned old = xb_add(&bar[XL_SUB(b.x)], 1u);
;         const unsigned gen = old / nloc;
;         if (old + 1u == (gen + 1u) * nloc) xb_add(&bar[XL_GEN(b.x)], 1u);
;         else XB_SPIN(xb_ld(&bar[XL_GEN(b.x)]) == gen, bar);
;         __builtin_amdgcn_fence(__ATOMIC_ACQUIRE, "agent");
;         asm volatile("s_waitcnt vmcnt(0)" ::: "memory");
.LBB0_725:
	s_or_b64 exec, exec, s[20:21]
	buffer_inv sc1
	s_waitcnt lgkmcnt(0)
	v_cvt_f32_u32_e32 v3, v0
	s_waitcnt vmcnt(1)
	v_readfirstlane_b32 s18, v2
	s_mov_b64 s[20:21], -1
	v_rcp_iflag_f32_e32 v3, v3
	v_add_u32_e32 v1, s18, v1
	v_add_u32_e32 v4, 1, v1
	s_add_u32 s18, s8, 0x4600
	v_mul_f32_e32 v2, 0x4f7ffffe, v3
	v_cvt_u32_f32_e32 v2, v2
	v_sub_u32_e32 v3, 0, v0
	s_addc_u32 s19, s9, 0
	v_mul_lo_u32 v3, v3, v2
	v_mul_hi_u32 v3, v2, v3
	v_add_u32_e32 v2, v2, v3
	v_mul_hi_u32 v2, v1, v2
	v_mul_lo_u32 v3, v2, v0
	v_sub_u32_e32 v1, v1, v3
	v_add_u32_e32 v5, 1, v2
	v_cmp_ge_u32_e32 vcc, v1, v0
	v_sub_u32_e32 v3, v1, v0
	s_nop 0
	v_cndmask_b32_e32 v2, v2, v5, vcc
	v_cndmask_b32_e32 v1, v1, v3, vcc
	v_add_u32_e32 v3, 1, v2
	v_cmp_ge_u32_e32 vcc, v1, v0
	s_nop 1
	v_cndmask_b32_e32 v2, v2, v3, vcc
	v_mul_lo_u32 v1, v0, v2
	v_add_u32_e32 v0, v1, v0
	v_cmp_ne_u32_e32 vcc, v4, v0
	v_mov_b64_e32 v[0:1], s[18:19]
	s_and_saveexec_b64 s[8:9], vcc
	s_cbranch_execz .LBB0_737
	v_mov_b32_e32 v0, 0
	global_load_dword v1, v0, s[18:19] sc1
	s_mov_b64 s[24:25], 0
	s_waitcnt vmcnt(0)
	v_cmp_eq_u32_e32 vcc, v1, v2
	s_and_saveexec_b64 s[22:23], vcc
	s_cbranch_execz .LBB0_736
	s_add_u32 s20, s50, 0x200
	s_addc_u32 s21, s51, 0
	s_mov_b32 s40, 1
	s_branch .LBB0_729

; __device__ __forceinline__ unsigned xb_ld(unsigned* p)              { return __hip_atomic_load(p, __ATOMIC_RELAXED, __HIP_MEMORY_SCOPE_AGENT); }
; __device__ __forceinline__ unsigned xb_add(unsigned* p, unsigned v) { return __hip_atomic_fetch_add(p, v, __ATOMIC_RELAXED, __HIP_MEMORY_SCOPE_AGENT); }
; #define XB_SPIN(cond, bar) do { unsigned _sp = 0; while (cond) { __builtin_amdgcn_s_sleep(1); \
;     if ((++_sp & 255u) == 0u) { if (xb_ld(&(bar)[XB_TMO])) break; if (_sp > XB_SPIN_CAP) { atomicAdd(&(bar)[XB_TMO], 1u); break; } } } } while (0)
; __device__ __forceinline__ void xcd_half_barrier(const XcdBarrier& b, unsigned h) {
;     ...
;         const unsigned old = xb_add(&bar[XB_XSUB(b.x)], 1u);
;         const unsigned gen = old / nloc;
;         if (old + 1u == (gen + 1u) * nloc) {
;             __builtin_amdgcn_fence(__ATOMIC_RELEASE, "agent");
;             asm volatile("s_waitcnt vmcnt(0)" ::: "memory");
;             const unsigned og = xb_add(&bar[XH_TOP(h)], 1u);
;             const unsigned tg = og / nx;
;             if (og + 1u == (tg + 1u) * nx) xb_add(&bar[XH_TOPGEN(h)], 1u);
;             else XB_SPIN(xb_ld(&bar[XH_TOPGEN(h)]) == tg, bar);
;             __builtin_amdgcn_fence(__ATOMIC_ACQUIRE, "agent");
;             xb_add(&bar[XB_XGEN(b.x)], 1u);
;             asm volatile("s_waitcnt vmcnt(0)" ::: "memory");
;         } else {
;             XB_SPIN(xb_ld(&bar[XB_XGEN(b.x)]) == gen, bar);
.LBB0_1415:
	s_or_b64 exec, exec, s[20:21]
	s_waitcnt lgkmcnt(0)
	v_cvt_f32_u32_e32 v3, v1
	s_waitcnt vmcnt(0)
	v_readfirstlane_b32 s18, v2
	v_sub_u32_e32 v2, 0, v1
	v_rcp_iflag_f32_e32 v3, v3
	v_add_u32_e32 v4, s18, v0
	v_mul_f32_e32 v3, 0x4f7ffffe, v3
	v_cvt_u32_f32_e32 v3, v3
	v_mul_lo_u32 v0, v2, v3
	v_mul_hi_u32 v0, v3, v0
	v_add_u32_e32 v0, v3, v0
	v_mul_hi_u32 v0, v4, v0
	v_mul_lo_u32 v2, v0, v1
	v_sub_u32_e32 v2, v4, v2
	v_add_u32_e32 v3, 1, v0
	v_cmp_ge_u32_e32 vcc, v2, v1
	s_nop 1
	v_cndmask_b32_e32 v0, v0, v3, vcc
	v_sub_u32_e32 v3, v2, v1
	v_cndmask_b32_e32 v2, v2, v3, vcc
	v_add_u32_e32 v3, 1, v0
	v_cmp_ge_u32_e32 vcc, v2, v1
	v_add_u32_e32 v2, 1, v4
	s_nop 0
	v_cndmask_b32_e32 v0, v0, v3, vcc
	v_mul_lo_u32 v3, v1, v0
	v_add_u32_e32 v1, v3, v1
	v_cmp_ne_u32_e32 vcc, v2, v1
	s_and_saveexec_b64 s[18:19], vcc
	s_xor_b64 s[18:19], exec, s[18:19]
	s_cbranch_execz .LBB0_1429
	buffer_inv sc1
	v_mov_b32_e32 v1, 0x2000
	global_load_dword v1, v1, s[8:9] offset:1024 sc1
	s_add_u32 s22, s8, 0x2400
	s_addc_u32 s23, s9, 0
	s_waitcnt vmcnt(0)
	v_cmp_eq_u32_e32 vcc, v1, v0
	s_and_saveexec_b64 s[20:21], vcc
	s_cbranch_execz .LBB0_1428
	s_mov_b32 s38, 1
	s_mov_b64 s[24:25], 0
	v_mov_b32_e32 v1, 0
	s_branch .LBB0_1419

; __device__ __forceinline__ unsigned xb_ld(unsigned* p)              { return __hip_atomic_load(p, __ATOMIC_RELAXED, __HIP_MEMORY_SCOPE_AGENT); }
; #define XB_SPIN(cond, bar) do { unsigned _sp = 0; while (cond) { __builtin_amdgcn_s_sleep(1); \
;     if ((++_sp & 255u) == 0u) { if (xb_ld(&(bar)[XB_TMO])) break; if (_sp > XB_SPIN_CAP) { atomicAdd(&(bar)[XB_TMO], 1u); break; } } } } while (0)
; __device__ __forceinline__ void xcd_half_barrier(const XcdBarrier& b, unsigned h) {
;     ...
;             XB_SPIN(xb_ld(&bar[XB_XGEN(b.x)]) == gen, bar);
;             __builtin_amdgcn_fence(__ATOMIC_ACQUIRE, "agent");
;             asm volatile("s_waitcnt vmcnt(0)" ::: "memory");
.LBB0_1428:
	s_or_b64 exec, exec, s[20:21]
	s_waitcnt vmcnt(0)
	s_waitcnt vmcnt(0)

; __device__ __forceinline__ unsigned xb_ld(unsigned* p)              { return __hip_atomic_load(p, __ATOMIC_RELAXED, __HIP_MEMORY_SCOPE_AGENT); }
; __device__ __forceinline__ unsigned xb_add(unsigned* p, unsigned v) { return __hip_atomic_fetch_add(p, v, __ATOMIC_RELAXED, __HIP_MEMORY_SCOPE_AGENT); }
; #define XB_SPIN(cond, bar) do { unsigned _sp = 0; while (cond) { __builtin_amdgcn_s_sleep(1); \
;     if ((++_sp & 255u) == 0u) { if (xb_ld(&(bar)[XB_TMO])) break; if (_sp > XB_SPIN_CAP) { atomicAdd(&(bar)[XB_TMO], 1u); break; } } } } while (0)
; __device__ __forceinline__ void xcd_local_barrier(const XcdBarrier& b) {
;     ...
;         const unsigned nloc = b.st[0];
;         const unsigned old = xb_add(&bar[XL_SUB(b.x)], 1u);
;         const unsigned gen = old / nloc;
;         if (old + 1u == (gen + 1u) * nloc) xb_add(&bar[XL_GEN(b.x)], 1u);
;         else XB_SPIN(xb_ld(&bar[XL_GEN(b.x)]) == gen, bar);
;         __builtin_amdgcn_fence(__ATOMIC_ACQUIRE, "agent");
;         asm volatile("s_waitcnt vmcnt(0)" ::: "memory");
.LBB0_1675:
	s_or_b64 exec, exec, s[18:19]
	buffer_inv sc1
	s_waitcnt lgkmcnt(0)
	v_cvt_f32_u32_e32 v3, v0
	s_waitcnt vmcnt(1)
	v_readfirstlane_b32 s14, v2
	s_mov_b64 s[18:19], -1
	v_rcp_iflag_f32_e32 v3, v3
	v_add_u32_e32 v1, s14, v1
	v_add_u32_e32 v4, 1, v1
	s_add_u32 s14, s8, 0x4600
	v_mul_f32_e32 v2, 0x4f7ffffe, v3
	v_cvt_u32_f32_e32 v2, v2
	v_sub_u32_e32 v3, 0, v0
	s_addc_u32 s15, s9, 0
	v_mul_lo_u32 v3, v3, v2
	v_mul_hi_u32 v3, v2, v3
	v_add_u32_e32 v2, v2, v3
	v_mul_hi_u32 v2, v1, v2
	v_mul_lo_u32 v3, v2, v0
	v_sub_u32_e32 v1, v1, v3
	v_add_u32_e32 v5, 1, v2
	v_cmp_ge_u32_e32 vcc, v1, v0
	v_sub_u32_e32 v3, v1, v0
	s_nop 0
	v_cndmask_b32_e32 v2, v2, v5, vcc
	v_cndmask_b32_e32 v1, v1, v3, vcc
	v_add_u32_e32 v3, 1, v2
	v_cmp_ge_u32_e32 vcc, v1, v0
	s_nop 1
	v_cndmask_b32_e32 v2, v2, v3, vcc
	v_mul_lo_u32 v1, v0, v2
	v_add_u32_e32 v0, v1, v0
	v_cmp_ne_u32_e32 vcc, v4, v0
	v_mov_b64_e32 v[0:1], s[14:15]
	s_and_saveexec_b64 s[8:9], vcc
	s_cbranch_execz .LBB0_1687
	v_mov_b32_e32 v0, 0
	global_load_dword v1, v0, s[14:15] sc1
	s_mov_b64 s[22:23], 0
	s_waitcnt vmcnt(0)
	v_cmp_eq_u32_e32 vcc, v1, v2
	s_and_saveexec_b64 s[20:21], vcc
	s_cbranch_execz .LBB0_1686
	s_add_u32 s18, s50, 0x200
	s_addc_u32 s19, s51, 0
	s_mov_b32 s34, 1
	s_branch .LBB0_1679

; __device__ __forceinline__ unsigned xb_ld(unsigned* p)              { return __hip_atomic_load(p, __ATOMIC_RELAXED, __HIP_MEMORY_SCOPE_AGENT); }
; __device__ __forceinline__ unsigned xb_add(unsigned* p, unsigned v) { return __hip_atomic_fetch_add(p, v, __ATOMIC_RELAXED, __HIP_MEMORY_SCOPE_AGENT); }
; #define XB_SPIN(cond, bar) do { unsigned _sp = 0; while (cond) { __builtin_amdgcn_s_sleep(1); \
;     if ((++_sp & 255u) == 0u) { if (xb_ld(&(bar)[XB_TMO])) break; if (_sp > XB_SPIN_CAP) { atomicAdd(&(bar)[XB_TMO], 1u); break; } } } } while (0)
; __device__ __forceinline__ void xcd_local_barrier(const XcdBarrier& b) {
;     ...
;         const unsigned nloc = b.st[0];
;         const unsigned old = xb_add(&bar[XL_SUB(b.x)], 1u);
;         const unsigned gen = old / nloc;
;         if (old + 1u == (gen + 1u) * nloc) xb_add(&bar[XL_GEN(b.x)], 1u);
;         else XB_SPIN(xb_ld(&bar[XL_GEN(b.x)]) == gen, bar);
;         __builtin_amdgcn_fence(__ATOMIC_ACQUIRE, "agent");
;         asm volatile("s_waitcnt vmcnt(0)" ::: "memory");
.LBB0_2159:
	s_or_b64 exec, exec, s[10:11]
	buffer_inv sc1
	s_waitcnt lgkmcnt(0)
	v_cvt_f32_u32_e32 v3, v0
	s_waitcnt vmcnt(1)
	v_readfirstlane_b32 s3, v2
	s_add_u32 s8, s0, 0x4600
	s_addc_u32 s9, s1, 0
	v_rcp_iflag_f32_e32 v3, v3
	v_add_u32_e32 v1, s3, v1
	v_add_u32_e32 v4, 1, v1
	s_mov_b64 s[10:11], -1
	v_mul_f32_e32 v2, 0x4f7ffffe, v3
	v_cvt_u32_f32_e32 v2, v2
	v_sub_u32_e32 v3, 0, v0
	v_mul_lo_u32 v3, v3, v2
	v_mul_hi_u32 v3, v2, v3
	v_add_u32_e32 v2, v2, v3
	v_mul_hi_u32 v2, v1, v2
	v_mul_lo_u32 v3, v2, v0
	v_sub_u32_e32 v1, v1, v3
	v_add_u32_e32 v5, 1, v2
	v_cmp_ge_u32_e32 vcc, v1, v0
	v_sub_u32_e32 v3, v1, v0
	s_nop 0
	v_cndmask_b32_e32 v2, v2, v5, vcc
	v_cndmask_b32_e32 v1, v1, v3, vcc
	v_add_u32_e32 v3, 1, v2
	v_cmp_ge_u32_e32 vcc, v1, v0
	s_nop 1
	v_cndmask_b32_e32 v2, v2, v3, vcc
	v_mul_lo_u32 v1, v0, v2
	v_add_u32_e32 v0, v1, v0
	v_cmp_ne_u32_e32 vcc, v4, v0
	v_mov_b64_e32 v[0:1], s[8:9]
	s_and_saveexec_b64 s[0:1], vcc
	s_cbranch_execz .LBB0_2171
	v_mov_b32_e32 v0, 0
	global_load_dword v1, v0, s[8:9] sc1
	s_mov_b64 s[14:15], 0
	s_waitcnt vmcnt(0)
	v_cmp_eq_u32_e32 vcc, v1, v2
	s_and_saveexec_b64 s[12:13], vcc
	s_cbranch_execz .LBB0_2170
	s_add_u32 s10, s50, 0x200
	s_addc_u32 s11, s51, 0
	s_mov_b32 s3, 1
	s_branch .LBB0_2163

; __device__ __forceinline__ unsigned xb_ld(unsigned* p)              { return __hip_atomic_load(p, __ATOMIC_RELAXED, __HIP_MEMORY_SCOPE_AGENT); }
; #define XB_SPIN(cond, bar) do { unsigned _sp = 0; while (cond) { __builtin_amdgcn_s_sleep(1); \
;     if ((++_sp & 255u) == 0u) { if (xb_ld(&(bar)[XB_TMO])) break; if (_sp > XB_SPIN_CAP) { atomicAdd(&(bar)[XB_TMO], 1u); break; } } } } while (0)
; __device__ __forceinline__ void xcd_local_barrier(const XcdBarrier& b) {
;     ...
;         else XB_SPIN(xb_ld(&bar[XL_GEN(b.x)]) == gen, bar);
;         __builtin_amdgcn_fence(__ATOMIC_ACQUIRE, "agent");
;         asm volatile("s_waitcnt vmcnt(0)" ::: "memory");
.LBB0_2173:
	s_or_b64 exec, exec, s[0:1]
	s_waitcnt vmcnt(0)
	s_waitcnt vmcnt(0)

; __global__ void __launch_bounds__(NTHR, 2) fwd_megakernel(Args a) {
;     ...
;     if (IN(15)) {
;         rowpass<true, false>(XB, YB, a.out, nullptr, a.g_ffn_post + D, mod + 2 * 6144 + 5120, nullptr, nullptr, nullptr, 6144, T, SEQ, G, bx);
;     }
;     ...
; }
.LBB0_2186:
	v_cmp_eq_u32_e32 vcc, 0, v206
	s_and_saveexec_b64 s[4:5], vcc
	s_cbranch_execz .Lflag_clr_done
	v_mov_b32_e32 v4, 0x5aa0
	v_mov_b32_e32 v2, 0
	v_mov_b32_e32 v3, 0
	global_store_dwordx2 v4, v[2:3], s[50:51] sc1
